# GEMM K-loop heads placed at fixed offsets inside a 64-byte line (p2align + s_nop pad): A1/B1/D1/E1 at 16, A2/E2 at 32; instruction stream otherwise identical to the previous best
# speedup vs baseline: 1.0175x; 1.0026x over previous
; template <class Epi, class Sched, bool ALIGN_EPI = false, bool SP2 = false>
; __device__ __forceinline__ void gemm_phase(PG8_LAS unsigned char* lds, const Gemm g, const Sched& S, const Epi& E) {
;     ...
;         const bool has_next = S.next(ui + 1, nxt);
;         const char* nA = has_next ? (const char*)g.A + (size_t)nxt.pm * tstep : cA; const char* nB = has_next ? (const char*)g.Bt + (size_t)nxt.pn * tstep : cB;
;     ...
; #pragma unroll
;         for (int a = 0; a < 2; ++a)
; #pragma unroll
;             for (int b = 0; b < 2; ++b)
; #pragma unroll
;                 for (int m = 0; m < 4; ++m)
; #pragma unroll
;                     for (int n = 0; n < 2; ++n) acc[a][b][m][n] = (f32x4){0.f, 0.f, 0.f, 0.f};
;         cur = nxt; cA = nA; cB = nB; ++ui;
.LBB0_79:
	s_ashr_i32 s25, s24, 31
	s_lshl_b64 s[26:27], s[24:25], 19
	s_add_u32 s26, s36, s26
	s_addc_u32 s27, s37, s27
	s_and_b64 s[28:29], s[4:5], exec
	s_cselect_b32 s25, s27, s7
	s_cselect_b32 s48, s26, s6
	s_ashr_i32 s23, s22, 31
	s_lshl_b64 s[28:29], s[22:23], 19
	s_add_u32 s28, s12, s28
	s_addc_u32 s29, s13, s29
	s_and_b64 s[34:35], s[4:5], exec
	s_cselect_b32 s23, s29, s31
	s_cselect_b32 s49, s28, s30
	s_add_u32 s6, s6, 0x40080
	s_addc_u32 s7, s7, 0
	s_add_u32 s56, s30, 0x100
	v_mov_b32_e32 v0, 0
	s_addc_u32 s57, s31, 0
	s_mov_b32 s58, -2
	v_mov_b32_e32 v1, v0
	v_mov_b32_e32 v2, v0
	v_mov_b32_e32 v3, v0
	v_mov_b32_e32 v8, v0
	v_mov_b32_e32 v9, v0
	v_mov_b32_e32 v10, v0
	v_mov_b32_e32 v11, v0
	v_mov_b32_e32 v16, v0
	v_mov_b32_e32 v17, v0
	v_mov_b32_e32 v18, v0
	v_mov_b32_e32 v19, v0
	v_mov_b32_e32 v24, v0
	v_mov_b32_e32 v25, v0
	v_mov_b32_e32 v26, v0
	v_mov_b32_e32 v27, v0
	v_mov_b32_e32 v32, v0
	v_mov_b32_e32 v33, v0
	v_mov_b32_e32 v34, v0
	v_mov_b32_e32 v35, v0
	v_mov_b32_e32 v40, v0
	v_mov_b32_e32 v41, v0
	v_mov_b32_e32 v42, v0
	v_mov_b32_e32 v43, v0
	v_mov_b32_e32 v48, v0
	v_mov_b32_e32 v49, v0
	v_mov_b32_e32 v50, v0
	v_mov_b32_e32 v51, v0
	v_mov_b32_e32 v56, v0
	v_mov_b32_e32 v57, v0
	v_mov_b32_e32 v58, v0
	v_mov_b32_e32 v59, v0
	v_mov_b32_e32 v4, v0
	v_mov_b32_e32 v5, v0
	v_mov_b32_e32 v6, v0
	v_mov_b32_e32 v7, v0
	v_mov_b32_e32 v12, v0
	v_mov_b32_e32 v13, v0
	v_mov_b32_e32 v14, v0
	v_mov_b32_e32 v15, v0
	v_mov_b32_e32 v20, v0
	v_mov_b32_e32 v21, v0
	v_mov_b32_e32 v22, v0
	v_mov_b32_e32 v23, v0
	v_mov_b32_e32 v28, v0
	v_mov_b32_e32 v29, v0
	v_mov_b32_e32 v30, v0
	v_mov_b32_e32 v31, v0
	v_mov_b32_e32 v36, v0
	v_mov_b32_e32 v37, v0
	v_mov_b32_e32 v38, v0
	v_mov_b32_e32 v39, v0
	v_mov_b32_e32 v44, v0
	v_mov_b32_e32 v45, v0
	v_mov_b32_e32 v46, v0
	v_mov_b32_e32 v47, v0
	v_mov_b32_e32 v52, v0
	v_mov_b32_e32 v53, v0
	v_mov_b32_e32 v54, v0
	v_mov_b32_e32 v55, v0
	v_mov_b32_e32 v60, v0
	v_mov_b32_e32 v61, v0
	v_mov_b32_e32 v62, v0
	v_mov_b32_e32 v63, v0
	v_mov_b32_e32 v64, v0
	v_mov_b32_e32 v65, v0
	v_mov_b32_e32 v66, v0
	v_mov_b32_e32 v67, v0
	v_mov_b32_e32 v72, v0
	v_mov_b32_e32 v73, v0
	v_mov_b32_e32 v74, v0
	v_mov_b32_e32 v75, v0
	v_mov_b32_e32 v80, v0
	v_mov_b32_e32 v81, v0
	v_mov_b32_e32 v82, v0
	v_mov_b32_e32 v83, v0
	v_mov_b32_e32 v88, v0
	v_mov_b32_e32 v89, v0
	v_mov_b32_e32 v90, v0
	v_mov_b32_e32 v91, v0
	v_mov_b32_e32 v96, v0
	v_mov_b32_e32 v97, v0
	v_mov_b32_e32 v98, v0
	v_mov_b32_e32 v99, v0
	v_mov_b32_e32 v104, v0
	v_mov_b32_e32 v105, v0
	v_mov_b32_e32 v106, v0
	v_mov_b32_e32 v107, v0
	v_mov_b32_e32 v112, v0
	v_mov_b32_e32 v113, v0
	v_mov_b32_e32 v114, v0
	v_mov_b32_e32 v115, v0
	v_mov_b32_e32 v120, v0
	v_mov_b32_e32 v121, v0
	v_mov_b32_e32 v122, v0
	v_mov_b32_e32 v123, v0
	v_mov_b32_e32 v68, v0
	v_mov_b32_e32 v69, v0
	v_mov_b32_e32 v70, v0
	v_mov_b32_e32 v71, v0
	v_mov_b32_e32 v76, v0
	v_mov_b32_e32 v77, v0
	v_mov_b32_e32 v78, v0
	v_mov_b32_e32 v79, v0
	v_mov_b32_e32 v84, v0
	v_mov_b32_e32 v85, v0
	v_mov_b32_e32 v86, v0
	v_mov_b32_e32 v87, v0
	v_mov_b32_e32 v92, v0
	v_mov_b32_e32 v93, v0
	v_mov_b32_e32 v94, v0
	v_mov_b32_e32 v95, v0
	v_mov_b32_e32 v100, v0
	v_mov_b32_e32 v101, v0
	v_mov_b32_e32 v102, v0
	v_mov_b32_e32 v103, v0
	v_mov_b32_e32 v108, v0
	v_mov_b32_e32 v109, v0
	v_mov_b32_e32 v110, v0
	v_mov_b32_e32 v111, v0
	v_mov_b32_e32 v116, v0
	v_mov_b32_e32 v117, v0
	v_mov_b32_e32 v118, v0
	v_mov_b32_e32 v119, v0
	v_mov_b32_e32 v124, v0
	v_mov_b32_e32 v125, v0
	v_mov_b32_e32 v126, v0
	v_mov_b32_e32 v127, v0
	.p2align 6
	s_nop 0
	s_nop 0
	s_nop 0
	s_nop 0

; template <class Epi, class Sched, bool ALIGN_EPI = false, bool SP2 = false>
; __device__ __forceinline__ void gemm_phase(PG8_LAS unsigned char* lds, const Gemm g, const Sched& S, const Epi& E) {
;     ...
; #pragma unroll
;         for (int a = 0; a < 2; ++a)
; #pragma unroll
;             for (int b = 0; b < 2; ++b)
; #pragma unroll
;                 for (int m = 0; m < 4; ++m)
; #pragma unroll
;                     for (int n = 0; n < 2; ++n) acc[a][b][m][n] = (f32x4){0.f, 0.f, 0.f, 0.f};
;         cur = nxt; cA = nA; cB = nB; ++ui;
.LBB0_162:
	s_add_u32 s44, s22, 0x100
	v_mov_b32_e32 v0, 0
	s_addc_u32 s45, s23, 0
	s_mov_b32 s46, -2
	v_mov_b32_e32 v1, v0
	v_mov_b32_e32 v2, v0
	v_mov_b32_e32 v3, v0
	v_mov_b32_e32 v4, v0
	v_mov_b32_e32 v5, v0
	v_mov_b32_e32 v6, v0
	v_mov_b32_e32 v7, v0
	v_mov_b32_e32 v8, v0
	v_mov_b32_e32 v9, v0
	v_mov_b32_e32 v10, v0
	v_mov_b32_e32 v11, v0
	v_mov_b32_e32 v16, v0
	v_mov_b32_e32 v17, v0
	v_mov_b32_e32 v18, v0
	v_mov_b32_e32 v19, v0
	v_mov_b32_e32 v24, v0
	v_mov_b32_e32 v25, v0
	v_mov_b32_e32 v26, v0
	v_mov_b32_e32 v27, v0
	v_mov_b32_e32 v32, v0
	v_mov_b32_e32 v33, v0
	v_mov_b32_e32 v34, v0
	v_mov_b32_e32 v35, v0
	v_mov_b32_e32 v40, v0
	v_mov_b32_e32 v41, v0
	v_mov_b32_e32 v42, v0
	v_mov_b32_e32 v43, v0
	v_mov_b32_e32 v48, v0
	v_mov_b32_e32 v49, v0
	v_mov_b32_e32 v50, v0
	v_mov_b32_e32 v51, v0
	v_mov_b32_e32 v12, v0
	v_mov_b32_e32 v13, v0
	v_mov_b32_e32 v14, v0
	v_mov_b32_e32 v15, v0
	v_mov_b32_e32 v20, v0
	v_mov_b32_e32 v21, v0
	v_mov_b32_e32 v22, v0
	v_mov_b32_e32 v23, v0
	v_mov_b32_e32 v28, v0
	v_mov_b32_e32 v29, v0
	v_mov_b32_e32 v30, v0
	v_mov_b32_e32 v31, v0
	v_mov_b32_e32 v36, v0
	v_mov_b32_e32 v37, v0
	v_mov_b32_e32 v38, v0
	v_mov_b32_e32 v39, v0
	v_mov_b32_e32 v44, v0
	v_mov_b32_e32 v45, v0
	v_mov_b32_e32 v46, v0
	v_mov_b32_e32 v47, v0
	v_mov_b32_e32 v52, v0
	v_mov_b32_e32 v53, v0
	v_mov_b32_e32 v54, v0
	v_mov_b32_e32 v55, v0
	v_mov_b32_e32 v56, v0
	v_mov_b32_e32 v57, v0
	v_mov_b32_e32 v58, v0
	v_mov_b32_e32 v59, v0
	v_mov_b32_e32 v60, v0
	v_mov_b32_e32 v61, v0
	v_mov_b32_e32 v62, v0
	v_mov_b32_e32 v63, v0
	v_mov_b32_e32 v64, v0
	v_mov_b32_e32 v65, v0
	v_mov_b32_e32 v66, v0
	v_mov_b32_e32 v67, v0
	v_mov_b32_e32 v68, v0
	v_mov_b32_e32 v69, v0
	v_mov_b32_e32 v70, v0
	v_mov_b32_e32 v71, v0
	v_mov_b32_e32 v72, v0
	v_mov_b32_e32 v73, v0
	v_mov_b32_e32 v74, v0
	v_mov_b32_e32 v75, v0
	v_mov_b32_e32 v80, v0
	v_mov_b32_e32 v81, v0
	v_mov_b32_e32 v82, v0
	v_mov_b32_e32 v83, v0
	v_mov_b32_e32 v88, v0
	v_mov_b32_e32 v89, v0
	v_mov_b32_e32 v90, v0
	v_mov_b32_e32 v91, v0
	v_mov_b32_e32 v96, v0
	v_mov_b32_e32 v97, v0
	v_mov_b32_e32 v98, v0
	v_mov_b32_e32 v99, v0
	v_mov_b32_e32 v104, v0
	v_mov_b32_e32 v105, v0
	v_mov_b32_e32 v106, v0
	v_mov_b32_e32 v107, v0
	v_mov_b32_e32 v112, v0
	v_mov_b32_e32 v113, v0
	v_mov_b32_e32 v114, v0
	v_mov_b32_e32 v115, v0
	v_mov_b32_e32 v76, v0
	v_mov_b32_e32 v77, v0
	v_mov_b32_e32 v78, v0
	v_mov_b32_e32 v79, v0
	v_mov_b32_e32 v84, v0
	v_mov_b32_e32 v85, v0
	v_mov_b32_e32 v86, v0
	v_mov_b32_e32 v87, v0
	v_mov_b32_e32 v92, v0
	v_mov_b32_e32 v93, v0
	v_mov_b32_e32 v94, v0
	v_mov_b32_e32 v95, v0
	v_mov_b32_e32 v100, v0
	v_mov_b32_e32 v101, v0
	v_mov_b32_e32 v102, v0
	v_mov_b32_e32 v103, v0
	v_mov_b32_e32 v108, v0
	v_mov_b32_e32 v109, v0
	v_mov_b32_e32 v110, v0
	v_mov_b32_e32 v111, v0
	v_mov_b32_e32 v116, v0
	v_mov_b32_e32 v117, v0
	v_mov_b32_e32 v118, v0
	v_mov_b32_e32 v119, v0
	v_mov_b32_e32 v120, v0
	v_mov_b32_e32 v121, v0
	v_mov_b32_e32 v122, v0
	v_mov_b32_e32 v123, v0
	v_mov_b32_e32 v124, v0
	v_mov_b32_e32 v125, v0
	v_mov_b32_e32 v126, v0
	v_mov_b32_e32 v127, v0
	.p2align 6
	s_nop 0
	s_nop 0
	s_nop 0
	s_nop 0
	s_nop 0
	s_nop 0
	s_nop 0
	s_nop 0

; template <class Epi, class Sched, bool ALIGN_EPI = false, bool SP2 = false>
; __device__ __forceinline__ void gemm_phase(PG8_LAS unsigned char* lds, const Gemm g, const Sched& S, const Epi& E) {
;     ...
;         const bool has_next = S.next(ui + 1, nxt);
;         const char* nA = has_next ? (const char*)g.A + (size_t)nxt.pm * tstep : cA; const char* nB = has_next ? (const char*)g.Bt + (size_t)nxt.pn * tstep : cB;
;     ...
; #pragma unroll
;         for (int a = 0; a < 2; ++a)
; #pragma unroll
;             for (int b = 0; b < 2; ++b)
; #pragma unroll
;                 for (int m = 0; m < 4; ++m)
; #pragma unroll
;                     for (int n = 0; n < 2; ++n) acc[a][b][m][n] = (f32x4){0.f, 0.f, 0.f, 0.f};
;         cur = nxt; cA = nA; cB = nB; ++ui;
.LBB0_303:
	s_ashr_i32 s19, s18, 31
	s_lshl_b64 s[20:21], s[18:19], 19
	s_add_u32 s20, s42, s20
	s_addc_u32 s21, s43, s21
	s_and_b64 s[22:23], s[10:11], exec
	s_cselect_b32 s19, s21, s25
	s_cselect_b32 s34, s20, s24
	s_ashr_i32 s7, s6, 31
	s_lshl_b64 s[22:23], s[6:7], 19
	s_add_u32 s22, s4, s22
	s_addc_u32 s23, s5, s23
	s_and_b64 s[28:29], s[10:11], exec
	s_cselect_b32 s7, s23, s27
	s_cselect_b32 s35, s22, s26
	s_add_u32 s24, s24, 0x40080
	s_addc_u32 s25, s25, 0
	s_add_u32 s36, s26, 0x100
	v_mov_b32_e32 v0, 0
	s_addc_u32 s37, s27, 0
	s_mov_b32 s84, -2
	v_mov_b32_e32 v1, v0
	v_mov_b32_e32 v2, v0
	v_mov_b32_e32 v3, v0
	v_mov_b32_e32 v4, v0
	v_mov_b32_e32 v5, v0
	v_mov_b32_e32 v6, v0
	v_mov_b32_e32 v7, v0
	v_mov_b32_e32 v16, v0
	v_mov_b32_e32 v17, v0
	v_mov_b32_e32 v18, v0
	v_mov_b32_e32 v19, v0
	v_mov_b32_e32 v20, v0
	v_mov_b32_e32 v21, v0
	v_mov_b32_e32 v22, v0
	v_mov_b32_e32 v23, v0
	v_mov_b32_e32 v32, v0
	v_mov_b32_e32 v33, v0
	v_mov_b32_e32 v34, v0
	v_mov_b32_e32 v35, v0
	v_mov_b32_e32 v36, v0
	v_mov_b32_e32 v37, v0
	v_mov_b32_e32 v38, v0
	v_mov_b32_e32 v39, v0
	v_mov_b32_e32 v48, v0
	v_mov_b32_e32 v49, v0
	v_mov_b32_e32 v50, v0
	v_mov_b32_e32 v51, v0
	v_mov_b32_e32 v52, v0
	v_mov_b32_e32 v53, v0
	v_mov_b32_e32 v54, v0
	v_mov_b32_e32 v55, v0
	v_mov_b32_e32 v8, v0
	v_mov_b32_e32 v9, v0
	v_mov_b32_e32 v10, v0
	v_mov_b32_e32 v11, v0
	v_mov_b32_e32 v12, v0
	v_mov_b32_e32 v13, v0
	v_mov_b32_e32 v14, v0
	v_mov_b32_e32 v15, v0
	v_mov_b32_e32 v24, v0
	v_mov_b32_e32 v25, v0
	v_mov_b32_e32 v26, v0
	v_mov_b32_e32 v27, v0
	v_mov_b32_e32 v28, v0
	v_mov_b32_e32 v29, v0
	v_mov_b32_e32 v30, v0
	v_mov_b32_e32 v31, v0
	v_mov_b32_e32 v40, v0
	v_mov_b32_e32 v41, v0
	v_mov_b32_e32 v42, v0
	v_mov_b32_e32 v43, v0
	v_mov_b32_e32 v44, v0
	v_mov_b32_e32 v45, v0
	v_mov_b32_e32 v46, v0
	v_mov_b32_e32 v47, v0
	v_mov_b32_e32 v56, v0
	v_mov_b32_e32 v57, v0
	v_mov_b32_e32 v58, v0
	v_mov_b32_e32 v59, v0
	v_mov_b32_e32 v60, v0
	v_mov_b32_e32 v61, v0
	v_mov_b32_e32 v62, v0
	v_mov_b32_e32 v63, v0
	v_mov_b32_e32 v64, v0
	v_mov_b32_e32 v65, v0
	v_mov_b32_e32 v66, v0
	v_mov_b32_e32 v67, v0
	v_mov_b32_e32 v68, v0
	v_mov_b32_e32 v69, v0
	v_mov_b32_e32 v70, v0
	v_mov_b32_e32 v71, v0
	v_mov_b32_e32 v80, v0
	v_mov_b32_e32 v81, v0
	v_mov_b32_e32 v82, v0
	v_mov_b32_e32 v83, v0
	v_mov_b32_e32 v84, v0
	v_mov_b32_e32 v85, v0
	v_mov_b32_e32 v86, v0
	v_mov_b32_e32 v87, v0
	v_mov_b32_e32 v96, v0
	v_mov_b32_e32 v97, v0
	v_mov_b32_e32 v98, v0
	v_mov_b32_e32 v99, v0
	v_mov_b32_e32 v100, v0
	v_mov_b32_e32 v101, v0
	v_mov_b32_e32 v102, v0
	v_mov_b32_e32 v103, v0
	v_mov_b32_e32 v112, v0
	v_mov_b32_e32 v113, v0
	v_mov_b32_e32 v114, v0
	v_mov_b32_e32 v115, v0
	v_mov_b32_e32 v116, v0
	v_mov_b32_e32 v117, v0
	v_mov_b32_e32 v118, v0
	v_mov_b32_e32 v119, v0
	v_mov_b32_e32 v72, v0
	v_mov_b32_e32 v73, v0
	v_mov_b32_e32 v74, v0
	v_mov_b32_e32 v75, v0
	v_mov_b32_e32 v76, v0
	v_mov_b32_e32 v77, v0
	v_mov_b32_e32 v78, v0
	v_mov_b32_e32 v79, v0
	v_mov_b32_e32 v88, v0
	v_mov_b32_e32 v89, v0
	v_mov_b32_e32 v90, v0
	v_mov_b32_e32 v91, v0
	v_mov_b32_e32 v92, v0
	v_mov_b32_e32 v93, v0
	v_mov_b32_e32 v94, v0
	v_mov_b32_e32 v95, v0
	v_mov_b32_e32 v104, v0
	v_mov_b32_e32 v105, v0
	v_mov_b32_e32 v106, v0
	v_mov_b32_e32 v107, v0
	v_mov_b32_e32 v108, v0
	v_mov_b32_e32 v109, v0
	v_mov_b32_e32 v110, v0
	v_mov_b32_e32 v111, v0
	v_mov_b32_e32 v120, v0
	v_mov_b32_e32 v121, v0
	v_mov_b32_e32 v122, v0
	v_mov_b32_e32 v123, v0
	v_mov_b32_e32 v124, v0
	v_mov_b32_e32 v125, v0
	v_mov_b32_e32 v126, v0
	v_mov_b32_e32 v127, v0
	.p2align 6
	s_nop 0
	s_nop 0
	s_nop 0
	s_nop 0

; template <class Epi, class Sched, bool ALIGN_EPI = false, bool SP2 = false>
; __device__ __forceinline__ void gemm_phase(PG8_LAS unsigned char* lds, const Gemm g, const Sched& S, const Epi& E) {
;     ...
;         const bool has_next = S.next(ui + 1, nxt);
;         const char* nA = has_next ? (const char*)g.A + (size_t)nxt.pm * tstep : cA; const char* nB = has_next ? (const char*)g.Bt + (size_t)nxt.pn * tstep : cB;
;     ...
; #pragma unroll
;         for (int a = 0; a < 2; ++a)
; #pragma unroll
;             for (int b = 0; b < 2; ++b)
; #pragma unroll
;                 for (int m = 0; m < 4; ++m)
; #pragma unroll
;                     for (int n = 0; n < 2; ++n) acc[a][b][m][n] = (f32x4){0.f, 0.f, 0.f, 0.f};
;         cur = nxt; cA = nA; cB = nB; ++ui;
.LBB0_1077:
	s_ashr_i32 s19, s18, 31
	s_lshl_b64 s[20:21], s[18:19], 19
	s_add_u32 s20, s30, s20
	s_addc_u32 s21, s31, s21
	s_and_b64 s[22:23], s[10:11], exec
	s_cselect_b32 s19, s21, s25
	s_cselect_b32 s44, s20, s24
	s_ashr_i32 s17, s16, 31
	s_lshl_b64 s[22:23], s[16:17], 19
	s_add_u32 s22, s4, s22
	s_addc_u32 s23, s5, s23
	s_and_b64 s[28:29], s[10:11], exec
	s_cselect_b32 s17, s23, s27
	s_cselect_b32 s45, s22, s26
	s_add_u32 s24, s24, 0x40080
	s_addc_u32 s25, s25, 0
	s_add_u32 s46, s26, 0x100
	v_mov_b32_e32 v0, 0
	s_addc_u32 s47, s27, 0
	s_mov_b32 s48, -2
	v_mov_b32_e32 v1, v0
	v_mov_b32_e32 v2, v0
	v_mov_b32_e32 v3, v0
	v_mov_b32_e32 v4, v0
	v_mov_b32_e32 v5, v0
	v_mov_b32_e32 v6, v0
	v_mov_b32_e32 v7, v0
	v_mov_b32_e32 v8, v0
	v_mov_b32_e32 v9, v0
	v_mov_b32_e32 v10, v0
	v_mov_b32_e32 v11, v0
	v_mov_b32_e32 v16, v0
	v_mov_b32_e32 v17, v0
	v_mov_b32_e32 v18, v0
	v_mov_b32_e32 v19, v0
	v_mov_b32_e32 v24, v0
	v_mov_b32_e32 v25, v0
	v_mov_b32_e32 v26, v0
	v_mov_b32_e32 v27, v0
	v_mov_b32_e32 v32, v0
	v_mov_b32_e32 v33, v0
	v_mov_b32_e32 v34, v0
	v_mov_b32_e32 v35, v0
	v_mov_b32_e32 v40, v0
	v_mov_b32_e32 v41, v0
	v_mov_b32_e32 v42, v0
	v_mov_b32_e32 v43, v0
	v_mov_b32_e32 v48, v0
	v_mov_b32_e32 v49, v0
	v_mov_b32_e32 v50, v0
	v_mov_b32_e32 v51, v0
	v_mov_b32_e32 v12, v0
	v_mov_b32_e32 v13, v0
	v_mov_b32_e32 v14, v0
	v_mov_b32_e32 v15, v0
	v_mov_b32_e32 v20, v0
	v_mov_b32_e32 v21, v0
	v_mov_b32_e32 v22, v0
	v_mov_b32_e32 v23, v0
	v_mov_b32_e32 v28, v0
	v_mov_b32_e32 v29, v0
	v_mov_b32_e32 v30, v0
	v_mov_b32_e32 v31, v0
	v_mov_b32_e32 v36, v0
	v_mov_b32_e32 v37, v0
	v_mov_b32_e32 v38, v0
	v_mov_b32_e32 v39, v0
	v_mov_b32_e32 v44, v0
	v_mov_b32_e32 v45, v0
	v_mov_b32_e32 v46, v0
	v_mov_b32_e32 v47, v0
	v_mov_b32_e32 v52, v0
	v_mov_b32_e32 v53, v0
	v_mov_b32_e32 v54, v0
	v_mov_b32_e32 v55, v0
	v_mov_b32_e32 v56, v0
	v_mov_b32_e32 v57, v0
	v_mov_b32_e32 v58, v0
	v_mov_b32_e32 v59, v0
	v_mov_b32_e32 v60, v0
	v_mov_b32_e32 v61, v0
	v_mov_b32_e32 v62, v0
	v_mov_b32_e32 v63, v0
	v_mov_b32_e32 v64, v0
	v_mov_b32_e32 v65, v0
	v_mov_b32_e32 v66, v0
	v_mov_b32_e32 v67, v0
	v_mov_b32_e32 v68, v0
	v_mov_b32_e32 v69, v0
	v_mov_b32_e32 v70, v0
	v_mov_b32_e32 v71, v0
	v_mov_b32_e32 v72, v0
	v_mov_b32_e32 v73, v0
	v_mov_b32_e32 v74, v0
	v_mov_b32_e32 v75, v0
	v_mov_b32_e32 v80, v0
	v_mov_b32_e32 v81, v0
	v_mov_b32_e32 v82, v0
	v_mov_b32_e32 v83, v0
	v_mov_b32_e32 v88, v0
	v_mov_b32_e32 v89, v0
	v_mov_b32_e32 v90, v0
	v_mov_b32_e32 v91, v0
	v_mov_b32_e32 v96, v0
	v_mov_b32_e32 v97, v0
	v_mov_b32_e32 v98, v0
	v_mov_b32_e32 v99, v0
	v_mov_b32_e32 v104, v0
	v_mov_b32_e32 v105, v0
	v_mov_b32_e32 v106, v0
	v_mov_b32_e32 v107, v0
	v_mov_b32_e32 v112, v0
	v_mov_b32_e32 v113, v0
	v_mov_b32_e32 v114, v0
	v_mov_b32_e32 v115, v0
	v_mov_b32_e32 v76, v0
	v_mov_b32_e32 v77, v0
	v_mov_b32_e32 v78, v0
	v_mov_b32_e32 v79, v0
	v_mov_b32_e32 v84, v0
	v_mov_b32_e32 v85, v0
	v_mov_b32_e32 v86, v0
	v_mov_b32_e32 v87, v0
	v_mov_b32_e32 v92, v0
	v_mov_b32_e32 v93, v0
	v_mov_b32_e32 v94, v0
	v_mov_b32_e32 v95, v0
	v_mov_b32_e32 v100, v0
	v_mov_b32_e32 v101, v0
	v_mov_b32_e32 v102, v0
	v_mov_b32_e32 v103, v0
	v_mov_b32_e32 v108, v0
	v_mov_b32_e32 v109, v0
	v_mov_b32_e32 v110, v0
	v_mov_b32_e32 v111, v0
	v_mov_b32_e32 v116, v0
	v_mov_b32_e32 v117, v0
	v_mov_b32_e32 v118, v0
	v_mov_b32_e32 v119, v0
	v_mov_b32_e32 v120, v0
	v_mov_b32_e32 v121, v0
	v_mov_b32_e32 v122, v0
	v_mov_b32_e32 v123, v0
	v_mov_b32_e32 v124, v0
	v_mov_b32_e32 v125, v0
	v_mov_b32_e32 v126, v0
	v_mov_b32_e32 v127, v0
	.p2align 6
	s_nop 0
	s_nop 0
	s_nop 0
	s_nop 0

; template <class Epi, class Sched, bool ALIGN_EPI = false, bool SP2 = false>
; __device__ __forceinline__ void gemm_phase(PG8_LAS unsigned char* lds, const Gemm g, const Sched& S, const Epi& E) {
;     ...
;         const bool has_next = S.next(ui + 1, nxt);
;         const char* nA = has_next ? (const char*)g.A + (size_t)nxt.pm * tstep : cA; const char* nB = has_next ? (const char*)g.Bt + (size_t)nxt.pn * tstep : cB;
;     ...
; #pragma unroll
;         for (int a = 0; a < 2; ++a)
; #pragma unroll
;             for (int b = 0; b < 2; ++b)
; #pragma unroll
;                 for (int m = 0; m < 4; ++m)
; #pragma unroll
;                     for (int n = 0; n < 2; ++n) acc[a][b][m][n] = (f32x4){0.f, 0.f, 0.f, 0.f};
;         cur = nxt; cA = nA; cB = nB; ++ui;
.LBB0_1218:
	s_ashr_i32 s21, s20, 31
	s_lshl_b64 s[22:23], s[20:21], 19
	s_add_u32 s22, s30, s22
	s_addc_u32 s23, s31, s23
	s_and_b64 s[24:25], s[10:11], exec
	s_cselect_b32 s21, s23, s7
	s_cselect_b32 s44, s22, s6
	s_ashr_i32 s19, s18, 31
	s_lshl_b64 s[24:25], s[18:19], 19
	s_add_u32 s24, s4, s24
	s_addc_u32 s25, s5, s25
	s_and_b64 s[28:29], s[10:11], exec
	s_cselect_b32 s19, s25, s27
	s_cselect_b32 s45, s24, s26
	s_add_u32 s6, s6, 0x40080
	s_addc_u32 s7, s7, 0
	s_add_u32 s46, s26, 0x100
	v_mov_b32_e32 v0, 0
	s_addc_u32 s47, s27, 0
	s_mov_b32 s48, -2
	v_mov_b32_e32 v1, v0
	v_mov_b32_e32 v2, v0
	v_mov_b32_e32 v3, v0
	v_mov_b32_e32 v8, v0
	v_mov_b32_e32 v9, v0
	v_mov_b32_e32 v10, v0
	v_mov_b32_e32 v11, v0
	v_mov_b32_e32 v16, v0
	v_mov_b32_e32 v17, v0
	v_mov_b32_e32 v18, v0
	v_mov_b32_e32 v19, v0
	v_mov_b32_e32 v24, v0
	v_mov_b32_e32 v25, v0
	v_mov_b32_e32 v26, v0
	v_mov_b32_e32 v27, v0
	v_mov_b32_e32 v32, v0
	v_mov_b32_e32 v33, v0
	v_mov_b32_e32 v34, v0
	v_mov_b32_e32 v35, v0
	v_mov_b32_e32 v40, v0
	v_mov_b32_e32 v41, v0
	v_mov_b32_e32 v42, v0
	v_mov_b32_e32 v43, v0
	v_mov_b32_e32 v48, v0
	v_mov_b32_e32 v49, v0
	v_mov_b32_e32 v50, v0
	v_mov_b32_e32 v51, v0
	v_mov_b32_e32 v56, v0
	v_mov_b32_e32 v57, v0
	v_mov_b32_e32 v58, v0
	v_mov_b32_e32 v59, v0
	v_mov_b32_e32 v4, v0
	v_mov_b32_e32 v5, v0
	v_mov_b32_e32 v6, v0
	v_mov_b32_e32 v7, v0
	v_mov_b32_e32 v12, v0
	v_mov_b32_e32 v13, v0
	v_mov_b32_e32 v14, v0
	v_mov_b32_e32 v15, v0
	v_mov_b32_e32 v20, v0
	v_mov_b32_e32 v21, v0
	v_mov_b32_e32 v22, v0
	v_mov_b32_e32 v23, v0
	v_mov_b32_e32 v28, v0
	v_mov_b32_e32 v29, v0
	v_mov_b32_e32 v30, v0
	v_mov_b32_e32 v31, v0
	v_mov_b32_e32 v36, v0
	v_mov_b32_e32 v37, v0
	v_mov_b32_e32 v38, v0
	v_mov_b32_e32 v39, v0
	v_mov_b32_e32 v44, v0
	v_mov_b32_e32 v45, v0
	v_mov_b32_e32 v46, v0
	v_mov_b32_e32 v47, v0
	v_mov_b32_e32 v52, v0
	v_mov_b32_e32 v53, v0
	v_mov_b32_e32 v54, v0
	v_mov_b32_e32 v55, v0
	v_mov_b32_e32 v60, v0
	v_mov_b32_e32 v61, v0
	v_mov_b32_e32 v62, v0
	v_mov_b32_e32 v63, v0
	v_mov_b32_e32 v64, v0
	v_mov_b32_e32 v65, v0
	v_mov_b32_e32 v66, v0
	v_mov_b32_e32 v67, v0
	v_mov_b32_e32 v72, v0
	v_mov_b32_e32 v73, v0
	v_mov_b32_e32 v74, v0
	v_mov_b32_e32 v75, v0
	v_mov_b32_e32 v80, v0
	v_mov_b32_e32 v81, v0
	v_mov_b32_e32 v82, v0
	v_mov_b32_e32 v83, v0
	v_mov_b32_e32 v88, v0
	v_mov_b32_e32 v89, v0
	v_mov_b32_e32 v90, v0
	v_mov_b32_e32 v91, v0
	v_mov_b32_e32 v96, v0
	v_mov_b32_e32 v97, v0
	v_mov_b32_e32 v98, v0
	v_mov_b32_e32 v99, v0
	v_mov_b32_e32 v104, v0
	v_mov_b32_e32 v105, v0
	v_mov_b32_e32 v106, v0
	v_mov_b32_e32 v107, v0
	v_mov_b32_e32 v112, v0
	v_mov_b32_e32 v113, v0
	v_mov_b32_e32 v114, v0
	v_mov_b32_e32 v115, v0
	v_mov_b32_e32 v120, v0
	v_mov_b32_e32 v121, v0
	v_mov_b32_e32 v122, v0
	v_mov_b32_e32 v123, v0
	v_mov_b32_e32 v68, v0
	v_mov_b32_e32 v69, v0
	v_mov_b32_e32 v70, v0
	v_mov_b32_e32 v71, v0
	v_mov_b32_e32 v76, v0
	v_mov_b32_e32 v77, v0
	v_mov_b32_e32 v78, v0
	v_mov_b32_e32 v79, v0
	v_mov_b32_e32 v84, v0
	v_mov_b32_e32 v85, v0
	v_mov_b32_e32 v86, v0
	v_mov_b32_e32 v87, v0
	v_mov_b32_e32 v92, v0
	v_mov_b32_e32 v93, v0
	v_mov_b32_e32 v94, v0
	v_mov_b32_e32 v95, v0
	v_mov_b32_e32 v100, v0
	v_mov_b32_e32 v101, v0
	v_mov_b32_e32 v102, v0
	v_mov_b32_e32 v103, v0
	v_mov_b32_e32 v108, v0
	v_mov_b32_e32 v109, v0
	v_mov_b32_e32 v110, v0
	v_mov_b32_e32 v111, v0
	v_mov_b32_e32 v116, v0
	v_mov_b32_e32 v117, v0
	v_mov_b32_e32 v118, v0
	v_mov_b32_e32 v119, v0
	v_mov_b32_e32 v124, v0
	v_mov_b32_e32 v125, v0
	v_mov_b32_e32 v126, v0
	v_mov_b32_e32 v127, v0
	.p2align 6
	s_nop 0
	s_nop 0
	s_nop 0
	s_nop 0
